# nt (non-temporal) hint on the read-once stream loads of P7 prep and P10 combine, on the aligned version
# speedup vs baseline: 1.0167x; 1.0167x over previous
.LBB0_46:
	v_add_u32_e32 v96, s34, v96
	v_cmp_gt_i32_e64 s[0:1], s98, v96
	v_cmp_lt_i32_e32 vcc, s99, v96
	s_and_saveexec_b64 s[40:41], s[0:1]
	s_cbranch_execz .LBB0_45
	v_ashrrev_i32_e32 v97, 31, v96
	v_lshlrev_b64 v[56:57], 10, v[96:97]
	v_readlane_b32 s0, v243, 5
	v_lshl_or_b32 v56, v98, 1, v56
	v_readlane_b32 s1, v243, 6
	v_lshl_add_u64 v[40:41], s[44:45], 0, v[56:57]
	v_lshl_add_u64 v[44:45], s[46:47], 0, v[56:57]
	v_lshl_add_u64 v[32:33], s[0:1], 0, v[56:57]
	v_readlane_b32 s0, v243, 11
	v_readlane_b32 s1, v243, 12
	v_lshl_add_u64 v[60:61], s[12:13], 0, v[56:57]
	s_nop 0
	v_lshl_add_u64 v[36:37], s[0:1], 0, v[56:57]
	v_readlane_b32 s0, v243, 7
	v_readlane_b32 s1, v243, 8
	global_load_dwordx4 v[32:35], v[32:33], off nt
	s_nop 0
	global_load_dwordx4 v[36:39], v[36:37], off nt
	v_lshl_add_u64 v[48:49], s[0:1], 0, v[56:57]
	v_readlane_b32 s0, v243, 15
	v_readlane_b32 s1, v243, 16
	global_load_dwordx4 v[40:43], v[40:41], off nt
	s_nop 0
	global_load_dwordx4 v[44:47], v[44:45], off nt
	v_lshl_add_u64 v[52:53], s[0:1], 0, v[56:57]
	v_readlane_b32 s0, v243, 13
	v_readlane_b32 s1, v243, 14
	global_load_dwordx4 v[48:51], v[48:49], off nt
	s_nop 0
	global_load_dwordx4 v[52:55], v[52:53], off nt
	v_lshl_add_u64 v[58:59], s[0:1], 0, v[56:57]
	global_load_dwordx4 v[56:59], v[58:59], off nt
	s_nop 0
	global_load_dwordx4 v[60:63], v[60:61], off nt
	s_branch .LBB0_45
